# as v43 plus attention: step bookkeeping (slot rotation, V-fragment address, pointer advance, rescale test) hoisted above the closing barrier of each step
# speedup vs baseline: 1.0050x; 1.0025x over previous
; #define WAIT_BAR(N) asm volatile("s_waitcnt vmcnt(" #N ") lgkmcnt(0)\n\ts_barrier":::"memory")
;   #define RESC() do{ if(resc){ asm volatile("s_waitcnt lgkmcnt(0)":::"memory"); \
;       _Pragma("unroll") for(int d_=0;d_<2;++d_) _Pragma("unroll") for(int r=0;r<16;++r)o[d_][r]*=wsf[crow(r,hi)]; } }while(0)
;   #define ROT() do{sl_prev=sl_cur;sl_cur=sl_next;sl_next=(sl_next==(NSLOT-1)*SLOTB)?0:sl_next+SLOTB;}while(0)
; template<int THRL> __device__ __forceinline__ void attn_unit(long rowbase,int NT,int q0,const bf16*Qh,const bf16*Kc,const bf16*Vc,bf16*Oh,char*shm,const float*rope,const float*qn){
;     ...
;   f32x16 pA0,pA1,pB0,pB1;
;   int sl_prev=0,sl_cur=0,sl_next=SLOTB;
;     ...
;   int t=1;
;   for(;t+5<NT;t+=2){
;     STEP(pB0,pB1,pA0,pA1,t,true,true,true);     WAIT_BAR(2); RESC(); ROT();
;     STEP(pA0,pA1,pB0,pB1,t+1,true,true,true);   WAIT_BAR(2); RESC(); ROT();
.LBB0_296:
	s_waitcnt lgkmcnt(14)
	v_mfma_f32_32x32x16_bf16 v[0:15], v[140:143], v[176:179], v[0:15]
	v_exp_f32_e32 v96, v96
	v_exp_f32_e32 v97, v97
	v_exp_f32_e32 v98, v98
	v_exp_f32_e32 v99, v99
	s_waitcnt lgkmcnt(12)
	v_mfma_f32_32x32x16_bf16 v[16:31], v[140:143], v[172:175], v[16:31]
	v_exp_f32_e32 v100, v100
	v_exp_f32_e32 v101, v101
	v_exp_f32_e32 v102, v102
	v_exp_f32_e32 v103, v103
	v_add_u32_e32 v76, s38, v251
	ds_read_b128 v[60:63], v76
	ds_read_b128 v[172:175], v76 offset:512
	s_waitcnt lgkmcnt(12)
	v_mfma_f32_32x32x16_bf16 v[0:15], v[136:139], v[64:67], v[0:15]
	v_exp_f32_e32 v104, v104
	v_exp_f32_e32 v105, v105
	v_exp_f32_e32 v106, v106
	v_exp_f32_e32 v107, v107
	ds_read_b128 v[176:179], v76 offset:2048
	ds_read_b128 v[168:171], v76 offset:2560
	s_waitcnt lgkmcnt(12)
	v_mfma_f32_32x32x16_bf16 v[16:31], v[136:139], v[68:71], v[16:31]
	v_exp_f32_e32 v108, v108
	v_exp_f32_e32 v109, v109
	v_exp_f32_e32 v110, v110
	v_exp_f32_e32 v111, v111
	ds_read_b128 v[164:167], v76 offset:4096
	ds_read_b128 v[160:163], v76 offset:4608
	s_waitcnt lgkmcnt(12)
	v_mfma_f32_32x32x16_bf16 v[0:15], v[128:131], v[72:75], v[0:15]
	v_exp_f32_e32 v80, v80
	v_exp_f32_e32 v81, v81
	v_exp_f32_e32 v82, v82
	v_exp_f32_e32 v83, v83
	ds_read_b128 v[156:159], v76 offset:6144
	ds_read_b128 v[152:155], v76 offset:6656
	s_waitcnt lgkmcnt(12)
	v_mfma_f32_32x32x16_bf16 v[16:31], v[128:131], v[48:51], v[16:31]
	v_exp_f32_e32 v84, v84
	v_exp_f32_e32 v85, v85
	v_exp_f32_e32 v86, v86
	v_exp_f32_e32 v87, v87
	s_waitcnt lgkmcnt(10)
	v_mfma_f32_32x32x16_bf16 v[0:15], v[124:127], v[52:55], v[0:15]
	v_exp_f32_e32 v88, v88
	v_exp_f32_e32 v89, v89
	v_exp_f32_e32 v90, v90
	v_exp_f32_e32 v91, v91
	s_waitcnt lgkmcnt(8)
	v_mfma_f32_32x32x16_bf16 v[16:31], v[124:127], v[56:59], v[16:31]
	v_exp_f32_e32 v92, v92
	v_exp_f32_e32 v93, v93
	v_exp_f32_e32 v94, v94
	v_exp_f32_e32 v95, v95
	s_add_i32 s0, s38, 0x2000
	s_cmpk_lg_i32 s38, 0x4000
	s_cselect_b32 s71, s0, 0
	v_add_u32_e32 v185, s43, v253
	s_andn2_b64 vcc, exec, s[36:37]
	s_waitcnt vmcnt(2) lgkmcnt(0)
	s_barrier
	s_cbranch_vccnz .LBB0_298
	s_waitcnt lgkmcnt(0)
	ds_read_b128 v[48:51], v249 offset:49248
	ds_read_b128 v[52:55], v249 offset:49216
	ds_read_b128 v[56:59], v249 offset:49184
	ds_read_b128 v[64:67], v249 offset:49152
	s_waitcnt lgkmcnt(3)
	v_pk_mul_f32 v[14:15], v[14:15], v[50:51]
	s_waitcnt lgkmcnt(2)
	v_pk_mul_f32 v[10:11], v[10:11], v[54:55]
	s_waitcnt lgkmcnt(1)
	v_pk_mul_f32 v[6:7], v[6:7], v[58:59]
	s_waitcnt lgkmcnt(0)
	v_pk_mul_f32 v[2:3], v[2:3], v[66:67]
	v_pk_mul_f32 v[12:13], v[12:13], v[48:49]
	v_pk_mul_f32 v[8:9], v[8:9], v[52:53]
	v_pk_mul_f32 v[4:5], v[4:5], v[56:57]
	v_pk_mul_f32 v[0:1], v[0:1], v[64:65]
	v_pk_mul_f32 v[30:31], v[30:31], v[50:51]
	v_pk_mul_f32 v[26:27], v[26:27], v[54:55]
	v_pk_mul_f32 v[22:23], v[22:23], v[58:59]
	v_pk_mul_f32 v[18:19], v[18:19], v[66:67]
	v_pk_mul_f32 v[28:29], v[28:29], v[48:49]
	v_pk_mul_f32 v[24:25], v[24:25], v[52:53]
	v_pk_mul_f32 v[20:21], v[20:21], v[56:57]
	v_pk_mul_f32 v[16:17], v[16:17], v[64:65]
.LBB0_298:
	ds_read_b64_tr_b16 v[148:149], v185 offset:24576
	ds_read_b64_tr_b16 v[150:151], v185 offset:25088
	s_waitcnt lgkmcnt(9)
	v_mfma_f32_32x32x16_bf16 v[64:79], v[60:63], v[116:119], v[32:47]
	v_add_f32_e32 v48, v96, v97
	v_add_f32_e32 v48, v98, v48
	v_add_f32_e32 v48, v99, v48
	v_add_f32_e32 v48, v100, v48
	v_add_f32_e32 v48, v101, v48
	v_cvt_pk_bf16_f32 v140, v96, v97
	v_cvt_pk_bf16_f32 v141, v98, v99
	ds_read_b64_tr_b16 v[144:145], v185 offset:28672
	ds_read_b64_tr_b16 v[146:147], v185 offset:29184
	v_add_f32_e32 v48, v102, v48
	v_add_f32_e32 v48, v103, v48
	v_add_f32_e32 v48, v104, v48
	v_add_f32_e32 v124, v105, v48
	s_waitcnt lgkmcnt(10)
	v_mfma_f32_32x32x16_bf16 v[48:63], v[172:175], v[116:119], v[32:47]
	v_cvt_pk_bf16_f32 v142, v100, v101
	v_cvt_pk_bf16_f32 v143, v102, v103
	ds_read_b64_tr_b16 v[96:97], v185 offset:25600
	ds_read_b64_tr_b16 v[98:99], v185 offset:26112
	s_waitcnt lgkmcnt(11)
	v_mfma_f32_32x32x16_bf16 v[64:79], v[176:179], v[112:115], v[64:79]
	v_add_f32_e32 v100, v106, v124
	v_add_f32_e32 v100, v107, v100
	v_add_f32_e32 v100, v108, v100
	v_add_f32_e32 v124, v109, v100
	v_cvt_pk_bf16_f32 v136, v104, v105
	v_cvt_pk_bf16_f32 v137, v106, v107
	ds_read_b64_tr_b16 v[100:101], v185 offset:29696
	ds_read_b64_tr_b16 v[102:103], v185 offset:30208
	s_waitcnt lgkmcnt(12)
	v_mfma_f32_32x32x16_bf16 v[48:63], v[168:171], v[112:115], v[48:63]
	v_add_f32_e32 v104, v110, v124
	v_add_f32_e32 v104, v111, v104
	v_add_f32_e32 v104, v80, v104
	v_add_f32_e32 v124, v81, v104
	v_cvt_pk_bf16_f32 v138, v108, v109
	v_cvt_pk_bf16_f32 v139, v110, v111
	ds_read_b64_tr_b16 v[104:105], v185 offset:26624
	ds_read_b64_tr_b16 v[106:107], v185 offset:27136
	s_waitcnt lgkmcnt(13)
	v_mfma_f32_32x32x16_bf16 v[64:79], v[164:167], v[120:123], v[64:79]
	v_add_f32_e32 v108, v82, v124
	v_add_f32_e32 v108, v83, v108
	v_add_f32_e32 v108, v84, v108
	v_add_f32_e32 v108, v85, v108
	v_cvt_pk_bf16_f32 v128, v80, v81
	v_cvt_pk_bf16_f32 v129, v82, v83
	ds_read_b64_tr_b16 v[80:81], v185 offset:30720
	ds_read_b64_tr_b16 v[82:83], v185 offset:31232
	s_waitcnt lgkmcnt(14)
	v_mfma_f32_32x32x16_bf16 v[48:63], v[160:163], v[120:123], v[48:63]
	v_add_f32_e32 v108, v86, v108
	v_add_f32_e32 v108, v87, v108
	v_add_f32_e32 v108, v88, v108
	v_add_f32_e32 v108, v89, v108
	v_cvt_pk_bf16_f32 v130, v84, v85
	v_cvt_pk_bf16_f32 v131, v86, v87
	ds_read_b64_tr_b16 v[84:85], v185 offset:27648
	ds_read_b64_tr_b16 v[86:87], v185 offset:28160
	s_waitcnt lgkmcnt(14)
	v_mfma_f32_32x32x16_bf16 v[64:79], v[156:159], v[132:135], v[64:79]
	v_add_f32_e32 v108, v90, v108
	v_add_f32_e32 v108, v91, v108
	v_add_f32_e32 v108, v92, v108
	v_add_f32_e32 v108, v93, v108
	v_cvt_pk_bf16_f32 v124, v88, v89
	v_cvt_pk_bf16_f32 v125, v90, v91
	ds_read_b64_tr_b16 v[88:89], v185 offset:31744
	ds_read_b64_tr_b16 v[90:91], v185 offset:32256
	v_mfma_f32_32x32x16_bf16 v[48:63], v[152:155], v[132:135], v[48:63]
	v_add_f32_e32 v108, v94, v108
	v_add_f32_e32 v108, v95, v108
	v_add_f32_e32 v108, 0, v108
	v_cvt_pk_bf16_f32 v126, v92, v93
	v_cvt_pk_bf16_f32 v127, v94, v95
	v_max_f32_e32 v92, v64, v65


	s_nop 6
	v_max3_f32 v93, v66, v67, v49
	v_max3_f32 v92, v92, v48, v50
	v_max3_f32 v92, v92, v51, v68
	v_max3_f32 v93, v93, v70, v71
	v_max3_f32 v92, v92, v69, v52
	v_max3_f32 v93, v93, v54, v55
	v_max3_f32 v92, v92, v53, v72
	v_max3_f32 v93, v93, v74, v75
	v_max3_f32 v92, v92, v73, v56
	v_max3_f32 v93, v93, v58, v59
	v_max3_f32 v92, v92, v57, v76
	v_max3_f32 v93, v93, v78, v79
	v_max3_f32 v92, v92, v77, v60
	v_max3_f32 v93, v93, v62, v63
	v_max3_f32 v92, v92, v61, v93
	v_mov_b32_e32 v93, v92
	s_nop 1
	v_permlane32_swap_b32_e32 v92, v93


; #define WAIT_BAR(N) asm volatile("s_waitcnt vmcnt(" #N ") lgkmcnt(0)\n\ts_barrier":::"memory")
;   #define RESC() do{ if(resc){ asm volatile("s_waitcnt lgkmcnt(0)":::"memory"); \
;       _Pragma("unroll") for(int d_=0;d_<2;++d_) _Pragma("unroll") for(int r=0;r<16;++r)o[d_][r]*=wsf[crow(r,hi)]; } }while(0)
;   #define ROT() do{sl_prev=sl_cur;sl_cur=sl_next;sl_next=(sl_next==(NSLOT-1)*SLOTB)?0:sl_next+SLOTB;}while(0)
; template<int THRL> __device__ __forceinline__ void attn_unit(long rowbase,int NT,int q0,const bf16*Qh,const bf16*Kc,const bf16*Vc,bf16*Oh,char*shm,const float*rope,const float*qn){
;     ...
;   int t=1;
;   for(;t+5<NT;t+=2){
;     STEP(pB0,pB1,pA0,pA1,t,true,true,true);     WAIT_BAR(2); RESC(); ROT();
;     STEP(pA0,pA1,pB0,pB1,t+1,true,true,true);   WAIT_BAR(2); RESC(); ROT();
	s_add_i32 s0, s38, s68
	s_mov_b32 s1, m0
	s_mov_b32 m0, s0
	s_nop 0
	global_load_lds_dwordx4 v[182:183], off
	s_mov_b32 m0, s1
	v_max_f32_e32 v92, v92, v93
	s_add_i32 s0, s71, s69
	s_mov_b32 s1, m0
	s_mov_b32 m0, s0
	s_nop 0
	global_load_lds_dwordx4 v[180:181], off
	s_mov_b32 m0, s1
	v_cmp_lt_f32_e32 vcc, s84, v92
	s_cmp_lg_u64 vcc, 0
	v_add_f32_e32 v237, v184, v108
	s_cselect_b64 s[36:37], -1, 0
	s_cbranch_vccnz .LBB0_306
.LBB0_299:
	s_waitcnt lgkmcnt(14)
	v_mfma_f32_32x32x16_bf16 v[0:15], v[140:143], v[148:151], v[0:15]
	v_exp_f32_e32 v64, v64
	v_exp_f32_e32 v65, v65
	v_exp_f32_e32 v66, v66
	v_exp_f32_e32 v67, v67
	s_waitcnt lgkmcnt(12)
	v_mfma_f32_32x32x16_bf16 v[16:31], v[140:143], v[144:147], v[16:31]
	v_exp_f32_e32 v68, v68
	v_exp_f32_e32 v69, v69
	v_exp_f32_e32 v70, v70
	v_exp_f32_e32 v71, v71
	v_add_u32_e32 v92, s71, v251
	ds_read_b128 v[172:175], v92
	ds_read_b128 v[168:171], v92 offset:512
	s_waitcnt lgkmcnt(12)
	v_mfma_f32_32x32x16_bf16 v[0:15], v[136:139], v[96:99], v[0:15]
	v_exp_f32_e32 v72, v72
	v_exp_f32_e32 v73, v73
	v_exp_f32_e32 v74, v74
	v_exp_f32_e32 v75, v75
	ds_read_b128 v[164:167], v92 offset:2048
	ds_read_b128 v[160:163], v92 offset:2560
	s_waitcnt lgkmcnt(12)
	v_mfma_f32_32x32x16_bf16 v[16:31], v[136:139], v[100:103], v[16:31]
	v_exp_f32_e32 v76, v76
	v_exp_f32_e32 v77, v77
	v_exp_f32_e32 v78, v78
	v_exp_f32_e32 v79, v79
	ds_read_b128 v[156:159], v92 offset:4096
	ds_read_b128 v[152:155], v92 offset:4608
	s_waitcnt lgkmcnt(12)
	v_mfma_f32_32x32x16_bf16 v[0:15], v[128:131], v[104:107], v[0:15]
	v_exp_f32_e32 v48, v48
	v_exp_f32_e32 v49, v49
	v_exp_f32_e32 v50, v50
	v_exp_f32_e32 v51, v51
	ds_read_b128 v[148:151], v92 offset:6144
	ds_read_b128 v[144:147], v92 offset:6656
	s_waitcnt lgkmcnt(12)
	v_mfma_f32_32x32x16_bf16 v[16:31], v[128:131], v[80:83], v[16:31]
	v_exp_f32_e32 v52, v52
	v_exp_f32_e32 v53, v53
	v_exp_f32_e32 v54, v54
	v_exp_f32_e32 v55, v55
	s_waitcnt lgkmcnt(10)
	v_mfma_f32_32x32x16_bf16 v[0:15], v[124:127], v[84:87], v[0:15]
	v_exp_f32_e32 v56, v56
	v_exp_f32_e32 v57, v57
	v_exp_f32_e32 v58, v58
	v_exp_f32_e32 v59, v59
	s_waitcnt lgkmcnt(8)
	v_mfma_f32_32x32x16_bf16 v[16:31], v[124:127], v[88:91], v[16:31]
	v_exp_f32_e32 v60, v60
	v_exp_f32_e32 v61, v61
	v_exp_f32_e32 v62, v62
	v_exp_f32_e32 v63, v63
	s_add_i32 s70, s70, 2
	s_add_i32 s0, s71, 0x2000
	s_cmpk_lg_i32 s71, 0x4000
	s_cselect_b32 s72, s0, 0
	v_lshl_add_u64 v[180:181], v[180:181], 0, s[96:97]
	v_lshl_add_u64 v[182:183], v[182:183], 0, s[96:97]
	s_andn2_b64 vcc, exec, s[36:37]
	s_waitcnt vmcnt(2) lgkmcnt(0)
	s_barrier
	s_cbranch_vccnz .LBB0_301
	s_waitcnt lgkmcnt(0)
	ds_read_b128 v[80:83], v249 offset:49248
	ds_read_b128 v[84:87], v249 offset:49216
	ds_read_b128 v[88:91], v249 offset:49184
	ds_read_b128 v[92:95], v249 offset:49152
	s_waitcnt lgkmcnt(3)
	v_pk_mul_f32 v[14:15], v[14:15], v[82:83]
	s_waitcnt lgkmcnt(2)
	v_pk_mul_f32 v[10:11], v[10:11], v[86:87]
	s_waitcnt lgkmcnt(1)
	v_pk_mul_f32 v[6:7], v[6:7], v[90:91]
	s_waitcnt lgkmcnt(0)
	v_pk_mul_f32 v[2:3], v[2:3], v[94:95]
	v_pk_mul_f32 v[12:13], v[12:13], v[80:81]
	v_pk_mul_f32 v[8:9], v[8:9], v[84:85]
	v_pk_mul_f32 v[4:5], v[4:5], v[88:89]
	v_pk_mul_f32 v[0:1], v[0:1], v[92:93]
	v_pk_mul_f32 v[30:31], v[30:31], v[82:83]
	v_pk_mul_f32 v[26:27], v[26:27], v[86:87]
	v_pk_mul_f32 v[22:23], v[22:23], v[90:91]
	v_pk_mul_f32 v[18:19], v[18:19], v[94:95]
	v_pk_mul_f32 v[28:29], v[28:29], v[80:81]
	v_pk_mul_f32 v[24:25], v[24:25], v[84:85]
	v_pk_mul_f32 v[20:21], v[20:21], v[88:89]
	v_pk_mul_f32 v[16:17], v[16:17], v[92:93]
.LBB0_301:
	s_add_i32 s0, s42, 2
	s_cmp_ge_u32 s70, s39
	v_lshl_add_u64 v[80:81], v[228:229], 0, s[96:97]
	v_lshl_add_u64 v[82:83], v[226:227], 0, s[96:97]
	s_cbranch_scc1 .LBB0_309
	v_mov_b64_e32 v[226:227], v[82:83]
	s_mov_b32 s42, s0
	v_mov_b64_e32 v[228:229], v[80:81]
	s_mov_b32 s0, s38
	s_mov_b32 s43, s71
	s_mov_b32 s38, s72
	s_branch .LBB0_295
